# scan1 state tile: MFMA operand roles swapped so each lane stores 4 consecutive values with one dwordx4
# speedup vs baseline: 1.0131x; 1.0005x over previous
; DEV f32x4 mfma16(bf16x8 a, bf16x8 b, f32x4 c) { return __builtin_amdgcn_mfma_f32_16x16x32_bf16(a, b, c, 0, 0, 0); }
; __device__ __forceinline__ void ph_scan1(const P& p, char* smem) {
;     ...
;       for (int t = wave; t < ntile; t += 4) {
;         int mt = t & 3, nt = t >> 2;
;         f32x4 acc = (f32x4){0.f, 0.f, 0.f, 0.f};
; #pragma unroll
;         for (int ks = 0; ks < 2; ks++) {
;           bf16x8 a = *(const bf16x8*)(sVT + (mt * 16 + lr) * 72 + ks * 32 + lq * 8);
;           bf16x8 bb = *(const bf16x8*)(sKT + (nt * 16 + lr) * 72 + ks * 32 + lq * 8);
;           acc = mfma16(a, bb, acc);
;         }
; #pragma unroll
;         for (int r = 0; r < 4; r++) outS[(mt * 16 + lq * 4 + r) * dk + nt * 16 + lr] = acc[r];
;       }
.LBB0_1350:
	s_or_b64 exec, exec, s[0:1]
	s_xor_b64 s[0:1], s[10:11], -1
	s_or_b32 s10, s26, s18
	s_mul_hi_i32 s11, s10, 36
	s_mul_i32 s10, s10, 36
	s_add_u32 s26, s10, s27
	s_addc_u32 s28, s11, s19
	s_waitcnt lgkmcnt(0)
	s_barrier
	s_and_saveexec_b64 s[10:11], s[6:7]
	s_cbranch_execz .LBB0_1353
	s_mul_i32 s12, s28, s22
	s_mul_hi_u32 s13, s26, s22
	ds_read_b128 v[0:3], v65 offset:16384
	ds_read_b128 v[4:7], v65 offset:16448
	s_add_i32 s13, s13, s12
	s_mul_i32 s12, s26, s22
	s_lshl_b64 s[12:13], s[12:13], 2
	s_add_u32 s12, s20, s12
	s_addc_u32 s13, s21, s13
	s_mov_b64 s[14:15], 0
	v_mov_b32_e32 v10, v64
	v_mov_b32_e32 v11, v43
	v_lshlrev_b32_e32 v25, 4, v43
	v_and_b32_e32 v25, 48, v25
	v_or_b32_e32 v25, v25, v47
	v_mul_u32_u24_e32 v25, s40, v25
	v_bfe_u32 v27, v40, 4, 2
	v_lshl_add_u32 v25, v27, 2, v25
.LBB0_1352:
	v_and_or_b32 v24, v10, -16, v47
	v_mad_u64_u32 v[16:17], s[34:35], v24, s33, v[42:43]
	ds_read_b128 v[12:15], v16 offset:25600
	ds_read_b128 v[20:23], v16 offset:25664
	v_and_b32_e32 v16, -16, v10
	v_add_u32_e32 v16, v16, v25
	v_ashrrev_i32_e32 v17, 31, v16
	s_waitcnt lgkmcnt(1)
	v_mfma_f32_16x16x32_bf16 v[12:15], v[12:15], v[0:3], 0
	v_add_u32_e32 v11, 4, v11
	v_cmp_le_i32_e32 vcc, s23, v11
	v_add_u32_e32 v10, 16, v10
	s_waitcnt lgkmcnt(0)
	v_mfma_f32_16x16x32_bf16 v[12:15], v[20:23], v[4:7], v[12:15]
	v_lshl_add_u64 v[20:21], v[16:17], 2, s[12:13]
	s_or_b64 s[14:15], vcc, s[14:15]
	s_nop 7
	global_store_dwordx4 v[20:21], v[12:15], off
	s_andn2_b64 exec, exec, s[14:15]
	s_cbranch_execnz .LBB0_1352
